# stepA + Fourier stage-B GEMM units dealt from the far end of the grid (balances the GLU+DFT interval in layer 1)
# speedup vs baseline: 1.0119x; 1.0079x over previous
; #define PG8_STAGE(bufoff, gbase, voff) do { _Pragma("unroll") for (int _i = 0; _i < 2; ++_i) \
;     __builtin_amdgcn_global_load_lds((const unsigned*)((const char*)(gbase) + (voff)[_i]), (LAS unsigned*)(lds + (bufoff) + ldsw + _i * 8192), 16, 0, 0); } while (0)
; #define PG8_WAIT_V(n) asm volatile("s_waitcnt vmcnt(" #n ")" ::: "memory")
; #define PG8_BAR __builtin_amdgcn_s_barrier()
;     ...
;   const char* cA = S.pA(cur); const char* cB = S.pB(cur);
;   PG8_STAGE(PG8_SB(0, 0), cB, voffB); PG8_STAGE(PG8_SB(0, 1), cB + hstepB, voffB); PG8_STAGE(PG8_SA(0, 0), cA, voffA); PG8_STAGE(PG8_SA(0, 1), cA + hstepA, voffA);
;   if (wr == 1) PG8_BAR;
;   PG8_WAIT_V(2); PG8_BAR;
;   PG8_STAGE(PG8_SB(1, 0), cB + kstep, voffB); PG8_STAGE(PG8_SA(1, 0), cA + kstep, voffA); PG8_STAGE(PG8_SB(1, 1), cB + hstepB + kstep, voffB);
;   PG8_WAIT_V(6); PG8_BAR;
.LBB0_798:
	s_sub_i32 s8, s26, s95
	s_add_i32 s8, s8, -1
	s_and_b64 s[0:1], s[48:49], exec
	v_mov_b32_e32 v1, v220
	s_cselect_b32 s0, s87, 0x80
	v_mov_b32_e32 v6, v220
	s_cmp_ge_i32 s8, s0
	v_readfirstlane_b32 s25, v6
	s_movk_i32 s76, 0x43ff
	s_mov_b32 s74, 0x19cd0000
	s_mov_b32 s75, 0x1a0d0000
	s_mov_b32 s77, 0x114d0000
	s_cbranch_scc1 .LBB0_816
	v_lshlrev_b32_e32 v1, 4, v6
	s_waitcnt vmcnt(0)
	v_add_u32_e32 v2, 0x2000, v1
	v_ashrrev_i32_e32 v3, 31, v2
	v_lshrrev_b32_e32 v3, 22, v3
	v_add_u32_e32 v3, v2, v3
	v_ashrrev_i32_e32 v7, 10, v3
	v_mul_i32_i24_e32 v4, 0x400, v7
	v_sub_u32_e32 v2, v2, v4
	v_lshrrev_b32_e32 v4, 4, v2
	v_bitop3_b32 v2, v4, v2, 32 bitop3:0x6c
	v_ashrrev_i32_e32 v4, 31, v2
	v_lshrrev_b32_e32 v4, 26, v4
	v_add_u32_e32 v4, v2, v4
	v_ashrrev_i32_e32 v8, 6, v4
	v_and_b32_e32 v4, 0xc0, v4
	v_sub_u32_e32 v2, v2, v4
	v_lshlrev_b32_e32 v3, 5, v7
	v_ashrrev_i16_sdwa v2, v224, sext(v2) dst_sel:DWORD dst_unused:UNUSED_PAD src0_sel:DWORD src1_sel:BYTE_0
	v_and_b32_e32 v3, 32, v3
	v_bfe_i32 v9, v2, 0, 16
	v_add_u32_e32 v2, v3, v9
	v_lshlrev_b32_e32 v3, 3, v7
	v_and_b32_e32 v3, 0x3ffff0, v3
	v_add_lshl_u32 v3, v8, v3, 10
	v_lshl_add_u32 v130, v2, 1, v3
	v_bfe_i32 v3, v6, 27, 1
	v_lshrrev_b32_e32 v3, 22, v3
	s_load_dwordx2 s[58:59], s[84:85], 0x108
	s_load_dwordx2 s[56:57], s[84:85], 0xe0
	v_add_u32_e32 v3, v1, v3
	v_and_b32_e32 v3, 0xfffffc00, v3
	v_sub_u32_e32 v1, v1, v3
	v_lshrrev_b32_e32 v3, 4, v1
	v_bitop3_b32 v1, v3, v1, 32 bitop3:0x6c
	s_waitcnt lgkmcnt(0)
	s_add_u32 s10, s58, 0xa080000
	v_ashrrev_i32_e32 v3, 31, v1
	s_addc_u32 s11, s59, 0
	v_ashrrev_i32_e32 v2, 31, v6
	v_lshrrev_b32_e32 v3, 26, v3
	s_add_u32 s1, s58, 0x19cd0000
	v_lshrrev_b32_e32 v2, 26, v2
	v_add_u32_e32 v3, v1, v3
	s_addc_u32 s2, s59, 0
	s_ashr_i32 s21, s25, 6
	s_ashr_i32 s9, s8, 31
	v_add_u32_e32 v2, v6, v2
	v_ashrrev_i32_e32 v11, 6, v3
	v_and_b32_e32 v3, 0xc0, v3
	s_ashr_i32 s24, s25, 8
	s_lshl_b32 s3, s21, 10
	v_ashrrev_i32_e32 v10, 6, v2
	v_sub_u32_e32 v1, v1, v3
	s_lshl_b64 s[4:5], s[8:9], 8
	s_lshl_b32 s9, s8, 8
	v_lshlrev_b32_e32 v2, 5, v10
	v_ashrrev_i16_sdwa v1, v224, sext(v1) dst_sel:DWORD dst_unused:UNUSED_PAD src0_sel:DWORD src1_sel:BYTE_0
	s_cmpk_lt_i32 s8, 0x80
	v_and_b32_e32 v2, 32, v2
	v_bfe_i32 v12, v1, 0, 16
	s_cselect_b32 s5, s5, 0
	s_cselect_b32 s4, s4, s9
	v_add_u32_e32 v1, v2, v12
	v_lshlrev_b32_e32 v2, 3, v10
	s_lshl_b64 s[4:5], s[4:5], 10
	v_and_b32_e32 v2, 0x3ffff0, v2
	s_add_u32 s12, s1, s4
	v_add_lshl_u32 v2, v11, v2, 10
	s_addc_u32 s13, s2, s5
	s_add_i32 s4, s3, 16
	v_lshl_add_u32 v132, v1, 1, v2
	s_add_i32 m0, s4, 0x10000
	v_mov_b32_e32 v133, v0
	global_load_lds_dwordx4 v132, s[12:13]
	s_add_i32 m0, s4, 0x12000
	s_add_u32 s14, s12, 0x20000
	global_load_lds_dwordx4 v130, s[12:13]
	s_addc_u32 s15, s13, 0
	s_add_i32 m0, s4, 0x14000
	s_add_i32 s5, s4, 0x2000
	global_load_lds_dwordx4 v132, s[14:15]
	s_add_i32 m0, s4, 0x16000
	v_mov_b32_e32 v131, v0
	global_load_lds_dwordx4 v130, s[14:15]
	s_mov_b32 m0, s4
	s_add_u32 s14, s58, 0xa0a0000
	global_load_lds_dwordx4 v132, s[10:11]
	s_mov_b32 m0, s5
	s_addc_u32 s15, s59, 0
	s_add_i32 s9, s4, 0x4000
	global_load_lds_dwordx4 v130, s[10:11]
	s_mov_b32 m0, s9
	s_add_i32 s18, s4, 0x6000
	global_load_lds_dwordx4 v132, s[14:15]
	s_mov_b32 m0, s18
	s_cmp_eq_u32 s24, 1
	global_load_lds_dwordx4 v130, s[14:15]
	v_lshl_add_u64 v[2:3], s[12:13], 0, v[132:133]
	s_cselect_b64 s[14:15], -1, 0
	s_cmp_lg_u32 s24, 1
	v_lshl_add_u64 v[4:5], s[12:13], 0, v[130:131]
	s_cbranch_scc1 .LBB0_801
	s_barrier
